# 64-byte alignment (.p2align 6) of the expert chunk loop header and the GEMM K-loop header, on top of the Q-early cross-attention stack
# speedup vs baseline: 1.0059x; 1.0026x over previous
; __device__ __forceinline__ void phase_expert(CArgs& A, int l, unsigned char* lds, int tid, bool dry = false) {
;     ...
;     for (int t = gw; t < T; t += NGW) {
;         f32x2 x[8], ff[8];
;         { float xf[16]; const bf16* xr = X + (size_t)t * DM + lane * 4;
; #pragma unroll
;           for (int i = 0; i < 4; ++i) { const u32x2 v = *(const u32x2*)(xr + 256 * i); xf[4 * i] = __uint_as_float(v.x << 16); xf[4 * i + 1] = __uint_as_float(v.x & 0xffff0000u); xf[4 * i + 2] = __uint_as_float(v.y << 16); xf[4 * i + 3] = __uint_as_float(v.y & 0xffff0000u); }
; #pragma unroll
;           for (int i = 0; i < 8; ++i) { x[i] = (f32x2){xf[2 * i], xf[2 * i + 1]}; ff[i] = (f32x2){0.f, 0.f}; } }
;         const int id0 = IDX[(size_t)t * 128 + lane], id1 = IDX[(size_t)t * 128 + 64 + lane];
;         const float gl0 = GATE[(size_t)t * 128 + lane], gl1 = GATE[(size_t)t * 128 + 64 + lane];
;         float xinv; int xh0 = 0, xh1 = 0, xl0 = 0, xl1 = 0;
;         { float am = 0.f;
; #pragma unroll
;           for (int i = 0; i < 8; ++i) am = fmaxf(am, fmaxf(fabsf(x[i].x), fabsf(x[i].y)));
; #pragma unroll
;           for (int o = 1; o < 64; o <<= 1) am = fmaxf(am, __shfl_xor(am, o));
;           const float xs = 119.f / fmaxf(am, 1e-20f); xinv = 1.f / (xs * U_SCALE);
; #pragma unroll
;           for (int i = 0; i < 16; ++i) { const float xv = (i & 1) ? x[i >> 1].y : x[i >> 1].x; const int q = (int)rintf(xv * xs);
;               const int lo = ((q + 8) & 15) - 8, hi = (q - lo) >> 4;
;               if (i < 8) { xl0 |= (lo & 15) << (4 * i); xh0 |= (hi & 15) << (4 * i); } else { xl1 |= (lo & 15) << (4 * (i - 8)); xh1 |= (hi & 15) << (4 * (i - 8)); } } }
;         u32x2 ur[2][8], vr[2][8]; float gtv[2];
.LBB0_41:
	v_ashrrev_i32_e32 v127, 31, v126
	v_lshlrev_b64 v[34:35], 11, v[126:127]
	v_lshl_add_u64 v[138:139], v[130:131], 0, v[34:35]
	v_lshlrev_b32_e32 v1, 9, v126
	v_lshl_or_b32 v1, v128, 2, v1
	global_load_dword v210, v1, s[6:7]
	global_load_dword v211, v1, s[6:7] offset:256
	global_load_dword v212, v1, s[56:57]
	global_load_dword v213, v1, s[56:57] offset:256
	global_load_dwordx2 v[34:35], v[138:139], off
	global_load_dwordx2 v[36:37], v[138:139], off offset:512
	global_load_dwordx2 v[38:39], v[138:139], off offset:1024
	global_load_dwordx2 v[40:41], v[138:139], off offset:1536
	s_mov_b32 s0, 0x1e3ce508
	s_mov_b32 s4, 0x42ee0000
	v_mov_b32_e32 v158, 0
	v_lshlrev_b64 v[136:137], 10, v[126:127]
	s_mov_b32 s8, 0
	v_mov_b32_e32 v159, v158
	v_mov_b32_e32 v160, v158
	v_mov_b32_e32 v161, v158
	s_waitcnt vmcnt(0)
	v_readlane_b32 s11, v210, 0
	s_lshl_b32 s11, s11, 10
	s_add_u32 s48, s72, s11
	s_addc_u32 s49, s73, 0
	global_load_dwordx4 v[80:83], v219, s[48:49]
	v_readlane_b32 s37, v210, 1
	s_lshl_b32 s37, s37, 10
	s_add_u32 s50, s72, s37
	s_addc_u32 s51, s73, 0
	global_load_dwordx4 v[84:87], v219, s[50:51]
	v_readlane_b32 s11, v210, 2
	s_lshl_b32 s11, s11, 10
	s_add_u32 s48, s72, s11
	s_addc_u32 s49, s73, 0
	global_load_dwordx4 v[88:91], v219, s[48:49]
	v_readlane_b32 s37, v210, 3
	s_lshl_b32 s37, s37, 10
	s_add_u32 s50, s72, s37
	s_addc_u32 s51, s73, 0
	global_load_dwordx4 v[92:95], v219, s[50:51]
	v_readlane_b32 s11, v210, 4
	s_lshl_b32 s11, s11, 10
	s_add_u32 s48, s72, s11
	s_addc_u32 s49, s73, 0
	global_load_dwordx4 v[96:99], v219, s[48:49]
	v_readlane_b32 s37, v210, 5
	s_lshl_b32 s37, s37, 10
	s_add_u32 s50, s72, s37
	s_addc_u32 s51, s73, 0
	global_load_dwordx4 v[100:103], v219, s[50:51]
	v_readlane_b32 s11, v210, 6
	s_lshl_b32 s11, s11, 10
	s_add_u32 s48, s72, s11
	s_addc_u32 s49, s73, 0
	global_load_dwordx4 v[104:107], v219, s[48:49]
	v_readlane_b32 s37, v210, 7
	s_lshl_b32 s37, s37, 10
	s_add_u32 s50, s72, s37
	s_addc_u32 s51, s73, 0
	global_load_dwordx4 v[108:111], v219, s[50:51]
	v_readlane_b32 s11, v210, 8
	s_lshl_b32 s11, s11, 10
	s_add_u32 s48, s72, s11
	s_addc_u32 s49, s73, 0
	global_load_dwordx4 v[112:115], v219, s[48:49]
	v_readlane_b32 s37, v210, 9
	s_lshl_b32 s37, s37, 10
	s_add_u32 s50, s72, s37
	s_addc_u32 s51, s73, 0
	global_load_dwordx4 v[116:119], v219, s[50:51]
	v_readlane_b32 s11, v210, 10
	s_lshl_b32 s11, s11, 10
	s_add_u32 s48, s72, s11
	s_addc_u32 s49, s73, 0
	global_load_dwordx4 v[120:123], v219, s[48:49]
	v_readlane_b32 s37, v210, 11
	s_lshl_b32 s37, s37, 10
	s_add_u32 s50, s72, s37
	s_addc_u32 s51, s73, 0
	global_load_dwordx4 v[220:223], v219, s[50:51]
	v_readlane_b32 s11, v210, 12
	s_lshl_b32 s11, s11, 10
	s_add_u32 s48, s72, s11
	s_addc_u32 s49, s73, 0
	global_load_dwordx4 v[224:227], v219, s[48:49]
	v_readlane_b32 s37, v210, 13
	s_lshl_b32 s37, s37, 10
	s_add_u32 s50, s72, s37
	s_addc_u32 s51, s73, 0
	global_load_dwordx4 v[228:231], v219, s[50:51]
	v_readlane_b32 s11, v210, 14
	s_lshl_b32 s11, s11, 10
	s_add_u32 s48, s72, s11
	s_addc_u32 s49, s73, 0
	global_load_dwordx4 v[232:235], v219, s[48:49]
	v_readlane_b32 s37, v210, 15
	s_lshl_b32 s37, s37, 10
	s_add_u32 s50, s72, s37
	s_addc_u32 s51, s73, 0
	global_load_dwordx4 v[236:239], v219, s[50:51]
	v_lshl_or_b32 v129, v210, 7, v128
	v_or_b32_e32 v42, 64, v128
	v_or_b32_e32 v43, 0xffffff80, v128
	v_cmp_gt_u32_e32 vcc, 24, v128
	v_lshl_or_b32 v132, v211, 7, v42
	s_nop 0
	v_cndmask_b32_e32 v129, v129, v43, vcc
	s_mov_b32 s74, 0x99999999
	s_mov_b32 s75, 0x99999999
	s_nop 1
	v_mov_b32_dpp v42, v129 quad_perm:[1,0,3,2] row_mask:0xf bank_mask:0xf
	v_mov_b32_dpp v43, v132 quad_perm:[1,0,3,2] row_mask:0xf bank_mask:0xf
	v_min_u32_e32 v44, v129, v42
	v_max_u32_e32 v45, v129, v42
	v_cndmask_b32_e64 v129, v45, v44, s[74:75]
	v_min_u32_e32 v44, v132, v43
	v_max_u32_e32 v45, v132, v43
	v_cndmask_b32_e64 v132, v45, v44, s[74:75]
	s_mov_b32 s74, 0xc3c3c3c3
	s_mov_b32 s75, 0xc3c3c3c3
	s_nop 1
	v_mov_b32_dpp v42, v129 quad_perm:[2,3,0,1] row_mask:0xf bank_mask:0xf
	v_mov_b32_dpp v43, v132 quad_perm:[2,3,0,1] row_mask:0xf bank_mask:0xf
	v_min_u32_e32 v44, v129, v42
	v_max_u32_e32 v45, v129, v42
	v_cndmask_b32_e64 v129, v45, v44, s[74:75]
	v_min_u32_e32 v44, v132, v43
	v_max_u32_e32 v45, v132, v43
	v_cndmask_b32_e64 v132, v45, v44, s[74:75]
	s_mov_b32 s74, 0xa5a5a5a5
	s_mov_b32 s75, 0xa5a5a5a5
	s_nop 1
	v_mov_b32_dpp v42, v129 quad_perm:[1,0,3,2] row_mask:0xf bank_mask:0xf
	v_mov_b32_dpp v43, v132 quad_perm:[1,0,3,2] row_mask:0xf bank_mask:0xf
	v_min_u32_e32 v44, v129, v42
	v_max_u32_e32 v45, v129, v42
	v_cndmask_b32_e64 v129, v45, v44, s[74:75]
	v_min_u32_e32 v44, v132, v43
	v_max_u32_e32 v45, v132, v43
	v_cndmask_b32_e64 v132, v45, v44, s[74:75]
	s_mov_b32 s74, 0xf00ff00f
	s_mov_b32 s75, 0xf00ff00f
	s_nop 1
	v_mov_b32_dpp v42, v129 row_shl:4 row_mask:0xf bank_mask:0x5
	s_nop 1
	v_mov_b32_dpp v42, v129 row_shr:4 row_mask:0xf bank_mask:0xa
	v_mov_b32_dpp v43, v132 row_shl:4 row_mask:0xf bank_mask:0x5
	s_nop 1
	v_mov_b32_dpp v43, v132 row_shr:4 row_mask:0xf bank_mask:0xa
	s_nop 0
	v_min_u32_e32 v44, v129, v42
	v_max_u32_e32 v45, v129, v42
	v_cndmask_b32_e64 v129, v45, v44, s[74:75]
	v_min_u32_e32 v44, v132, v43
	v_max_u32_e32 v45, v132, v43
	v_cndmask_b32_e64 v132, v45, v44, s[74:75]
	s_mov_b32 s74, 0xcc33cc33
	s_mov_b32 s75, 0xcc33cc33
	s_nop 1
	v_mov_b32_dpp v42, v129 quad_perm:[2,3,0,1] row_mask:0xf bank_mask:0xf
	v_mov_b32_dpp v43, v132 quad_perm:[2,3,0,1] row_mask:0xf bank_mask:0xf
	v_min_u32_e32 v44, v129, v42
	v_max_u32_e32 v45, v129, v42
	v_cndmask_b32_e64 v129, v45, v44, s[74:75]
	v_min_u32_e32 v44, v132, v43
	v_max_u32_e32 v45, v132, v43
	v_cndmask_b32_e64 v132, v45, v44, s[74:75]
; __device__ __forceinline__ void phase_expert(CArgs& A, int l, unsigned char* lds, int tid, bool dry = false) {
;     ...
;         const int id0 = IDX[(size_t)t * 128 + lane], id1 = IDX[(size_t)t * 128 + 64 + lane];
;         const float gl0 = GATE[(size_t)t * 128 + lane], gl1 = GATE[(size_t)t * 128 + 64 + lane];
	s_mov_b32 s74, 0xaa55aa55
	s_mov_b32 s75, 0xaa55aa55
	s_nop 1
	v_mov_b32_dpp v42, v129 quad_perm:[1,0,3,2] row_mask:0xf bank_mask:0xf
	v_mov_b32_dpp v43, v132 quad_perm:[1,0,3,2] row_mask:0xf bank_mask:0xf
	v_min_u32_e32 v44, v129, v42
	v_max_u32_e32 v45, v129, v42
	v_cndmask_b32_e64 v129, v45, v44, s[74:75]
	v_min_u32_e32 v44, v132, v43
	v_max_u32_e32 v45, v132, v43
	v_cndmask_b32_e64 v132, v45, v44, s[74:75]
	s_mov_b32 s74, 0xff0000ff
	s_mov_b32 s75, 0xff0000ff
	s_nop 1
	v_mov_b32_dpp v42, v129 row_ror:8 row_mask:0xf bank_mask:0xf
	v_mov_b32_dpp v43, v132 row_ror:8 row_mask:0xf bank_mask:0xf
	v_min_u32_e32 v44, v129, v42
	v_max_u32_e32 v45, v129, v42
	v_cndmask_b32_e64 v129, v45, v44, s[74:75]
	v_min_u32_e32 v44, v132, v43
	v_max_u32_e32 v45, v132, v43
	v_cndmask_b32_e64 v132, v45, v44, s[74:75]
	s_mov_b32 s74, 0xf0f00f0f
	s_mov_b32 s75, 0xf0f00f0f
	s_nop 1
	v_mov_b32_dpp v42, v129 row_shl:4 row_mask:0xf bank_mask:0x5
	s_nop 1
	v_mov_b32_dpp v42, v129 row_shr:4 row_mask:0xf bank_mask:0xa
	v_mov_b32_dpp v43, v132 row_shl:4 row_mask:0xf bank_mask:0x5
	s_nop 1
	v_mov_b32_dpp v43, v132 row_shr:4 row_mask:0xf bank_mask:0xa
	s_nop 0
	v_min_u32_e32 v44, v129, v42
	v_max_u32_e32 v45, v129, v42
	v_cndmask_b32_e64 v129, v45, v44, s[74:75]
	v_min_u32_e32 v44, v132, v43
	v_max_u32_e32 v45, v132, v43
	v_cndmask_b32_e64 v132, v45, v44, s[74:75]
	s_mov_b32 s74, 0xcccc3333
	s_mov_b32 s75, 0xcccc3333
	s_nop 1
	v_mov_b32_dpp v42, v129 quad_perm:[2,3,0,1] row_mask:0xf bank_mask:0xf
	v_mov_b32_dpp v43, v132 quad_perm:[2,3,0,1] row_mask:0xf bank_mask:0xf
	v_min_u32_e32 v44, v129, v42
	v_max_u32_e32 v45, v129, v42
	v_cndmask_b32_e64 v129, v45, v44, s[74:75]
	v_min_u32_e32 v44, v132, v43
	v_max_u32_e32 v45, v132, v43
	v_cndmask_b32_e64 v132, v45, v44, s[74:75]
	s_mov_b32 s74, 0xaaaa5555
	s_mov_b32 s75, 0xaaaa5555
	s_nop 1
	v_mov_b32_dpp v42, v129 quad_perm:[1,0,3,2] row_mask:0xf bank_mask:0xf
	v_mov_b32_dpp v43, v132 quad_perm:[1,0,3,2] row_mask:0xf bank_mask:0xf
	v_min_u32_e32 v44, v129, v42
	v_max_u32_e32 v45, v129, v42
	v_cndmask_b32_e64 v129, v45, v44, s[74:75]
	v_min_u32_e32 v44, v132, v43
	v_max_u32_e32 v45, v132, v43
	v_cndmask_b32_e64 v132, v45, v44, s[74:75]
	s_mov_b32 s74, 0xffff
	s_mov_b32 s75, 0xffff0000
	ds_bpermute_b32 v42, v195, v129
	ds_bpermute_b32 v43, v195, v132
	s_waitcnt lgkmcnt(0)
	v_min_u32_e32 v44, v129, v42
	v_max_u32_e32 v45, v129, v42
	v_cndmask_b32_e64 v129, v45, v44, s[74:75]
	v_min_u32_e32 v44, v132, v43
	v_max_u32_e32 v45, v132, v43
	v_cndmask_b32_e64 v132, v45, v44, s[74:75]
	s_mov_b32 s74, 0xff00ff
	s_mov_b32 s75, 0xff00ff00
	s_nop 1
	v_mov_b32_dpp v42, v129 row_ror:8 row_mask:0xf bank_mask:0xf
	v_mov_b32_dpp v43, v132 row_ror:8 row_mask:0xf bank_mask:0xf
	v_min_u32_e32 v44, v129, v42
	v_max_u32_e32 v45, v129, v42
	v_cndmask_b32_e64 v129, v45, v44, s[74:75]
	v_min_u32_e32 v44, v132, v43
	v_max_u32_e32 v45, v132, v43
	v_cndmask_b32_e64 v132, v45, v44, s[74:75]
	s_mov_b32 s74, 0xf0f0f0f
	s_mov_b32 s75, 0xf0f0f0f0
	s_nop 1
	v_mov_b32_dpp v42, v129 row_shl:4 row_mask:0xf bank_mask:0x5
	s_nop 1
	v_mov_b32_dpp v42, v129 row_shr:4 row_mask:0xf bank_mask:0xa
	v_mov_b32_dpp v43, v132 row_shl:4 row_mask:0xf bank_mask:0x5
	s_nop 1
	v_mov_b32_dpp v43, v132 row_shr:4 row_mask:0xf bank_mask:0xa
	s_nop 0
	v_min_u32_e32 v44, v129, v42
	v_max_u32_e32 v45, v129, v42
	v_cndmask_b32_e64 v129, v45, v44, s[74:75]
	v_min_u32_e32 v44, v132, v43
	v_max_u32_e32 v45, v132, v43
	v_cndmask_b32_e64 v132, v45, v44, s[74:75]
	s_mov_b32 s74, 0x33333333
	s_mov_b32 s75, 0xcccccccc
	s_nop 1
	v_mov_b32_dpp v42, v129 quad_perm:[2,3,0,1] row_mask:0xf bank_mask:0xf
	v_mov_b32_dpp v43, v132 quad_perm:[2,3,0,1] row_mask:0xf bank_mask:0xf
	v_min_u32_e32 v44, v129, v42
	v_max_u32_e32 v45, v129, v42
	v_cndmask_b32_e64 v129, v45, v44, s[74:75]
	v_min_u32_e32 v44, v132, v43
	v_max_u32_e32 v45, v132, v43
	v_cndmask_b32_e64 v132, v45, v44, s[74:75]
	s_mov_b32 s74, 0x55555555
	s_mov_b32 s75, 0xaaaaaaaa
	s_nop 1
	v_mov_b32_dpp v42, v129 quad_perm:[1,0,3,2] row_mask:0xf bank_mask:0xf
	v_mov_b32_dpp v43, v132 quad_perm:[1,0,3,2] row_mask:0xf bank_mask:0xf
	v_min_u32_e32 v44, v129, v42
	v_max_u32_e32 v45, v129, v42
	v_cndmask_b32_e64 v129, v45, v44, s[74:75]
	v_min_u32_e32 v44, v132, v43
	v_max_u32_e32 v45, v132, v43
	v_cndmask_b32_e64 v132, v45, v44, s[74:75]
	s_mov_b32 s74, 0xffffffff
	s_mov_b32 s75, 0x0
	s_mov_b32 s48, 0x0
	s_mov_b32 s49, 0xffffffff
	ds_bpermute_b32 v42, v196, v129
	ds_bpermute_b32 v43, v196, v132
	s_waitcnt lgkmcnt(0)
	v_min_u32_e32 v44, v129, v42
	v_max_u32_e32 v45, v129, v42
	v_cndmask_b32_e64 v129, v45, v44, s[74:75]
	v_min_u32_e32 v44, v132, v43
	v_max_u32_e32 v45, v132, v43
	v_cndmask_b32_e64 v132, v45, v44, s[48:49]
	s_mov_b32 s74, 0xffff
	s_mov_b32 s75, 0xffff
	s_mov_b32 s48, 0xffff0000
	s_mov_b32 s49, 0xffff0000
	ds_bpermute_b32 v42, v195, v129
	ds_bpermute_b32 v43, v195, v132
	s_waitcnt lgkmcnt(0)
; __device__ __forceinline__ void phase_expert(CArgs& A, int l, unsigned char* lds, int tid, bool dry = false) {
;     ...
;         const int id0 = IDX[(size_t)t * 128 + lane], id1 = IDX[(size_t)t * 128 + 64 + lane];
;         const float gl0 = GATE[(size_t)t * 128 + lane], gl1 = GATE[(size_t)t * 128 + 64 + lane];
	v_min_u32_e32 v44, v129, v42
	v_max_u32_e32 v45, v129, v42
	v_cndmask_b32_e64 v129, v45, v44, s[74:75]
	v_min_u32_e32 v44, v132, v43
	v_max_u32_e32 v45, v132, v43
	v_cndmask_b32_e64 v132, v45, v44, s[48:49]
	s_mov_b32 s74, 0xff00ff
	s_mov_b32 s75, 0xff00ff
	s_mov_b32 s48, 0xff00ff00
	s_mov_b32 s49, 0xff00ff00
	s_nop 1
	v_mov_b32_dpp v42, v129 row_ror:8 row_mask:0xf bank_mask:0xf
	v_mov_b32_dpp v43, v132 row_ror:8 row_mask:0xf bank_mask:0xf
	v_min_u32_e32 v44, v129, v42
	v_max_u32_e32 v45, v129, v42
	v_cndmask_b32_e64 v129, v45, v44, s[74:75]
	v_min_u32_e32 v44, v132, v43
	v_max_u32_e32 v45, v132, v43
	v_cndmask_b32_e64 v132, v45, v44, s[48:49]
	s_mov_b32 s74, 0xf0f0f0f
	s_mov_b32 s75, 0xf0f0f0f
	s_mov_b32 s48, 0xf0f0f0f0
	s_mov_b32 s49, 0xf0f0f0f0
	s_nop 1
	v_mov_b32_dpp v42, v129 row_shl:4 row_mask:0xf bank_mask:0x5
	s_nop 1
	v_mov_b32_dpp v42, v129 row_shr:4 row_mask:0xf bank_mask:0xa
	v_mov_b32_dpp v43, v132 row_shl:4 row_mask:0xf bank_mask:0x5
	s_nop 1
	v_mov_b32_dpp v43, v132 row_shr:4 row_mask:0xf bank_mask:0xa
	s_nop 0
	v_min_u32_e32 v44, v129, v42
	v_max_u32_e32 v45, v129, v42
	v_cndmask_b32_e64 v129, v45, v44, s[74:75]
	v_min_u32_e32 v44, v132, v43
	v_max_u32_e32 v45, v132, v43
	v_cndmask_b32_e64 v132, v45, v44, s[48:49]
	s_mov_b32 s74, 0x33333333
	s_mov_b32 s75, 0x33333333
	s_mov_b32 s48, 0xcccccccc
	s_mov_b32 s49, 0xcccccccc
	s_nop 1
	v_mov_b32_dpp v42, v129 quad_perm:[2,3,0,1] row_mask:0xf bank_mask:0xf
	v_mov_b32_dpp v43, v132 quad_perm:[2,3,0,1] row_mask:0xf bank_mask:0xf
	v_min_u32_e32 v44, v129, v42
	v_max_u32_e32 v45, v129, v42
	v_cndmask_b32_e64 v129, v45, v44, s[74:75]
	v_min_u32_e32 v44, v132, v43
	v_max_u32_e32 v45, v132, v43
	v_cndmask_b32_e64 v132, v45, v44, s[48:49]
	s_mov_b32 s74, 0x55555555
	s_mov_b32 s75, 0x55555555
	s_mov_b32 s48, 0xaaaaaaaa
	s_mov_b32 s49, 0xaaaaaaaa
	s_nop 1
	v_mov_b32_dpp v42, v129 quad_perm:[1,0,3,2] row_mask:0xf bank_mask:0xf
	v_mov_b32_dpp v43, v132 quad_perm:[1,0,3,2] row_mask:0xf bank_mask:0xf
	v_min_u32_e32 v44, v129, v42
	v_max_u32_e32 v45, v129, v42
	v_cndmask_b32_e64 v129, v45, v44, s[74:75]
	v_min_u32_e32 v44, v132, v43
	v_max_u32_e32 v45, v132, v43
	v_cndmask_b32_e64 v132, v45, v44, s[48:49]
	v_min_u32_e32 v44, v129, v132
	v_max_u32_e32 v132, v129, v132
	v_mov_b32_e32 v129, v44
	s_mov_b32 s74, 0xffffffff
	s_mov_b32 s75, 0x0
	ds_bpermute_b32 v42, v196, v129
	ds_bpermute_b32 v43, v196, v132
	s_waitcnt lgkmcnt(0)
	v_min_u32_e32 v44, v129, v42
	v_max_u32_e32 v45, v129, v42
	v_cndmask_b32_e64 v129, v45, v44, s[74:75]
	v_min_u32_e32 v44, v132, v43
	v_max_u32_e32 v45, v132, v43
	v_cndmask_b32_e64 v132, v45, v44, s[74:75]
	s_mov_b32 s74, 0xffff
	s_mov_b32 s75, 0xffff
	ds_bpermute_b32 v42, v195, v129
	ds_bpermute_b32 v43, v195, v132
	s_waitcnt lgkmcnt(0)
	v_min_u32_e32 v44, v129, v42
	v_max_u32_e32 v45, v129, v42
	v_cndmask_b32_e64 v129, v45, v44, s[74:75]
	v_min_u32_e32 v44, v132, v43
	v_max_u32_e32 v45, v132, v43
	v_cndmask_b32_e64 v132, v45, v44, s[74:75]
	s_mov_b32 s74, 0xff00ff
	s_mov_b32 s75, 0xff00ff
	s_nop 1
	v_mov_b32_dpp v42, v129 row_ror:8 row_mask:0xf bank_mask:0xf
	v_mov_b32_dpp v43, v132 row_ror:8 row_mask:0xf bank_mask:0xf
	v_min_u32_e32 v44, v129, v42
	v_max_u32_e32 v45, v129, v42
	v_cndmask_b32_e64 v129, v45, v44, s[74:75]
	v_min_u32_e32 v44, v132, v43
	v_max_u32_e32 v45, v132, v43
	v_cndmask_b32_e64 v132, v45, v44, s[74:75]
	s_mov_b32 s74, 0xf0f0f0f
	s_mov_b32 s75, 0xf0f0f0f
	s_nop 1
	v_mov_b32_dpp v42, v129 row_shl:4 row_mask:0xf bank_mask:0x5
	s_nop 1
	v_mov_b32_dpp v42, v129 row_shr:4 row_mask:0xf bank_mask:0xa
	v_mov_b32_dpp v43, v132 row_shl:4 row_mask:0xf bank_mask:0x5
	s_nop 1
	v_mov_b32_dpp v43, v132 row_shr:4 row_mask:0xf bank_mask:0xa
	s_nop 0
	v_min_u32_e32 v44, v129, v42
	v_max_u32_e32 v45, v129, v42
	v_cndmask_b32_e64 v129, v45, v44, s[74:75]
	v_min_u32_e32 v44, v132, v43
	v_max_u32_e32 v45, v132, v43
	v_cndmask_b32_e64 v132, v45, v44, s[74:75]
	s_mov_b32 s74, 0x33333333
	s_mov_b32 s75, 0x33333333
	s_nop 1
	v_mov_b32_dpp v42, v129 quad_perm:[2,3,0,1] row_mask:0xf bank_mask:0xf
	v_mov_b32_dpp v43, v132 quad_perm:[2,3,0,1] row_mask:0xf bank_mask:0xf
	v_min_u32_e32 v44, v129, v42
	v_max_u32_e32 v45, v129, v42
	v_cndmask_b32_e64 v129, v45, v44, s[74:75]
	v_min_u32_e32 v44, v132, v43
	v_max_u32_e32 v45, v132, v43
	v_cndmask_b32_e64 v132, v45, v44, s[74:75]
	s_mov_b32 s74, 0x55555555
	s_mov_b32 s75, 0x55555555
	s_nop 1
	v_mov_b32_dpp v42, v129 quad_perm:[1,0,3,2] row_mask:0xf bank_mask:0xf
	v_mov_b32_dpp v43, v132 quad_perm:[1,0,3,2] row_mask:0xf bank_mask:0xf
	v_min_u32_e32 v44, v129, v42
	v_max_u32_e32 v45, v129, v42
	v_cndmask_b32_e64 v129, v45, v44, s[74:75]
	v_min_u32_e32 v44, v132, v43
	v_max_u32_e32 v45, v132, v43
	v_cndmask_b32_e64 v132, v45, v44, s[74:75]
	v_and_b32_e32 v46, 63, v129
	v_and_b32_e32 v47, 63, v132
	v_lshlrev_b32_e32 v46, 2, v46
	v_lshlrev_b32_e32 v47, 2, v47
	ds_bpermute_b32 v48, v46, v212
	ds_bpermute_b32 v49, v46, v213
	ds_bpermute_b32 v50, v47, v212
	ds_bpermute_b32 v51, v47, v213
	v_and_b32_e32 v46, 64, v129
	v_and_b32_e32 v47, 64, v132
	v_cmp_eq_u32_e64 s[74:75], 0, v46
	v_cmp_eq_u32_e64 s[48:49], 0, v47
	v_lshrrev_b32_e32 v129, 7, v129
	v_lshrrev_b32_e32 v132, 7, v132
	s_waitcnt lgkmcnt(0)
; __device__ __forceinline__ void phase_expert(CArgs& A, int l, unsigned char* lds, int tid, bool dry = false) {
;     ...
;         { float xf[16]; const bf16* xr = X + (size_t)t * DM + lane * 4;
; #pragma unroll
;           for (int i = 0; i < 4; ++i) { const u32x2 v = *(const u32x2*)(xr + 256 * i); xf[4 * i] = __uint_as_float(v.x << 16); xf[4 * i + 1] = __uint_as_float(v.x & 0xffff0000u); xf[4 * i + 2] = __uint_as_float(v.y << 16); xf[4 * i + 3] = __uint_as_float(v.y & 0xffff0000u); }
; #pragma unroll
;           for (int i = 0; i < 8; ++i) { x[i] = (f32x2){xf[2 * i], xf[2 * i + 1]}; ff[i] = (f32x2){0.f, 0.f}; } }
;         const int id0 = IDX[(size_t)t * 128 + lane], id1 = IDX[(size_t)t * 128 + 64 + lane];
;         const float gl0 = GATE[(size_t)t * 128 + lane], gl1 = GATE[(size_t)t * 128 + 64 + lane];
;         float xinv; int xh0 = 0, xh1 = 0, xl0 = 0, xl1 = 0;
;         { float am = 0.f;
; #pragma unroll
;           for (int i = 0; i < 8; ++i) am = fmaxf(am, fmaxf(fabsf(x[i].x), fabsf(x[i].y)));
; #pragma unroll
;           for (int o = 1; o < 64; o <<= 1) am = fmaxf(am, __shfl_xor(am, o));
	v_cndmask_b32_e64 v133, v49, v48, s[74:75]
	v_cndmask_b32_e64 v1, v51, v50, s[48:49]
	v_lshlrev_b32_e32 v156, 16, v34
	v_and_b32_e32 v157, 0xffff0000, v34
	v_lshlrev_b32_e32 v154, 16, v35
	v_and_b32_e32 v155, 0xffff0000, v35
	v_lshlrev_b32_e32 v152, 16, v36
	v_and_b32_e32 v153, 0xffff0000, v36
	v_lshlrev_b32_e32 v150, 16, v37
	v_and_b32_e32 v151, 0xffff0000, v37
	v_max_f32_e64 v34, |v157|, |v157|
	v_max_f32_e64 v35, |v156|, |v156|
	v_max_f32_e64 v36, |v155|, |v155|
	v_max_f32_e64 v37, |v154|, |v154|
	v_lshlrev_b32_e32 v148, 16, v38
	v_and_b32_e32 v149, 0xffff0000, v38
	v_lshlrev_b32_e32 v146, 16, v39
	v_and_b32_e32 v147, 0xffff0000, v39
	v_lshlrev_b32_e32 v144, 16, v40
	v_and_b32_e32 v145, 0xffff0000, v40
	v_lshlrev_b32_e32 v140, 16, v41
	v_and_b32_e32 v141, 0xffff0000, v41
	v_max_f32_e64 v38, |v153|, |v153|
	v_max_f32_e64 v39, |v152|, |v152|
	v_max_f32_e64 v40, |v151|, |v151|
	v_max_f32_e64 v41, |v150|, |v150|
	v_max_f32_e32 v34, v35, v34
	v_max_f32_e32 v35, v37, v36
	v_max_f32_e64 v42, |v149|, |v149|
	v_max_f32_e64 v43, |v148|, |v148|
	v_max_f32_e64 v44, |v147|, |v147|
	v_max_f32_e64 v45, |v146|, |v146|
	v_max_f32_e32 v36, v39, v38
	v_max_f32_e32 v37, v41, v40
	v_max3_f32 v34, v34, 0, v35
	v_max_f32_e64 v46, |v145|, |v145|
	v_max_f32_e64 v47, |v144|, |v144|
	v_max_f32_e64 v48, |v141|, |v141|
	v_max_f32_e64 v49, |v140|, |v140|
	v_max_f32_e32 v38, v43, v42
	v_max_f32_e32 v39, v45, v44
	v_max3_f32 v34, v34, v36, v37
	v_max_f32_e32 v40, v47, v46
	v_max_f32_e32 v41, v49, v48
	v_max3_f32 v34, v34, v38, v39
	v_max3_f32 v34, v34, v40, v41
	ds_bpermute_b32 v35, v143, v34
	s_waitcnt lgkmcnt(0)
	v_max_f32_e32 v35, v35, v35
	v_max_f32_e32 v34, v34, v35
	ds_bpermute_b32 v35, v192, v34
	s_waitcnt lgkmcnt(0)
	v_max_f32_e32 v35, v35, v35
	v_max_f32_e32 v34, v34, v35
	ds_bpermute_b32 v35, v193, v34
	s_waitcnt lgkmcnt(0)
	v_max_f32_e32 v35, v35, v35
	v_max_f32_e32 v34, v34, v35
	ds_bpermute_b32 v35, v194, v34
	s_waitcnt lgkmcnt(0)
	v_max_f32_e32 v35, v35, v35
	v_max_f32_e32 v36, v34, v35
	ds_bpermute_b32 v40, v195, v36
	s_waitcnt lgkmcnt(0)
	v_max_f32_e32 v40, v40, v40
	v_max_f32_e32 v42, v36, v40
	ds_bpermute_b32 v43, v196, v42
	s_waitcnt lgkmcnt(0)
; __device__ __forceinline__ void phase_expert(CArgs& A, int l, unsigned char* lds, int tid, bool dry = false) {
;     ...
;         float xinv; int xh0 = 0, xh1 = 0, xl0 = 0, xl1 = 0;
;         { float am = 0.f;
; #pragma unroll
;           for (int i = 0; i < 8; ++i) am = fmaxf(am, fmaxf(fabsf(x[i].x), fabsf(x[i].y)));
; #pragma unroll
;           for (int o = 1; o < 64; o <<= 1) am = fmaxf(am, __shfl_xor(am, o));
;           const float xs = 119.f / fmaxf(am, 1e-20f); xinv = 1.f / (xs * U_SCALE);
; #pragma unroll
;           for (int i = 0; i < 16; ++i) { const float xv = (i & 1) ? x[i >> 1].y : x[i >> 1].x; const int q = (int)rintf(xv * xs);
;               const int lo = ((q + 8) & 15) - 8, hi = (q - lo) >> 4;
;               if (i < 8) { xl0 |= (lo & 15) << (4 * i); xh0 |= (hi & 15) << (4 * i); } else { xl1 |= (lo & 15) << (4 * (i - 8)); xh1 |= (hi & 15) << (4 * (i - 8)); } } }
;         u32x2 ur[2][8], vr[2][8]; float gtv[2];
	v_max3_f32 v42, v42, v43, s0
	v_div_scale_f32 v43, s[0:1], v42, v42, s4
	v_rcp_f32_e32 v44, v43
	v_div_scale_f32 v34, vcc, s4, v42, s4
	v_fma_f32 v35, -v43, v44, 1.0
	v_fmac_f32_e32 v44, v35, v44
	v_mul_f32_e32 v35, v34, v44
	v_fma_f32 v36, -v43, v35, v34
	v_fmac_f32_e32 v35, v36, v44
	v_fma_f32 v34, -v43, v35, v34
	v_div_fmas_f32 v34, v34, v44, v35
	v_div_fixup_f32 v38, v34, v42, s4
	v_mul_f32_e32 v34, v38, v156
	v_mul_f32_e32 v35, v38, v157
	v_mul_f32_e32 v36, v38, v154
	v_mul_f32_e32 v37, v38, v155
	v_rndne_f32_e32 v34, v34
	v_rndne_f32_e32 v35, v35
	v_rndne_f32_e32 v36, v36
	v_rndne_f32_e32 v37, v37
	v_cvt_i32_f32_e32 v34, v34
	v_cvt_i32_f32_e32 v35, v35
	v_cvt_i32_f32_e32 v36, v36
	v_cvt_i32_f32_e32 v37, v37
	v_mul_f32_e32 v40, v38, v152
	v_mul_f32_e32 v41, v38, v153
	v_rndne_f32_e32 v40, v40
	v_bfe_i32 v44, v34, 0, 4
	v_bfe_i32 v45, v35, 0, 4
	v_bfe_i32 v47, v36, 0, 4
	v_bfe_i32 v49, v37, 0, 4
	v_mul_f32_e32 v42, v38, v150
	v_rndne_f32_e32 v41, v41
	v_cvt_i32_f32_e32 v40, v40
	v_lshlrev_b32_e32 v46, 4, v35
	v_lshlrev_b32_e32 v48, 8, v36
	v_lshlrev_b32_e32 v50, 12, v37
	v_sub_u32_e32 v44, v34, v44
	v_sub_u32_e32 v35, v35, v45
	v_sub_u32_e32 v36, v36, v47
	v_sub_u32_e32 v37, v37, v49
	v_rndne_f32_e32 v42, v42
	v_cvt_i32_f32_e32 v41, v41
	v_lshrrev_b32_e32 v44, 4, v44
	v_and_b32_e32 v35, 0xf0, v35
	v_lshlrev_b32_e32 v36, 4, v36
	v_lshlrev_b32_e32 v37, 8, v37
	v_mul_f32_e32 v43, v38, v151
	v_cvt_i32_f32_e32 v42, v42
	v_and_or_b32 v35, v44, 15, v35
	v_and_b32_e32 v36, 0xf00, v36
	v_and_b32_e32 v37, 0xf000, v37
	v_or3_b32 v35, v35, v36, v37
	v_rndne_f32_e32 v36, v43
	v_bfe_i32 v51, v40, 0, 4
	v_cvt_i32_f32_e32 v36, v36
	v_lshlrev_b32_e32 v52, 16, v40
	v_bfe_i32 v53, v41, 0, 4
	v_sub_u32_e32 v40, v40, v51
	v_lshlrev_b32_e32 v54, 20, v41
	v_bfe_i32 v55, v42, 0, 4
	v_and_b32_e32 v45, 0xf0, v46
	v_sub_u32_sdwa v41, v41, v53 dst_sel:WORD_1 dst_unused:UNUSED_PAD src0_sel:DWORD src1_sel:DWORD
	v_lshlrev_b32_e32 v40, 12, v40
	v_lshlrev_b32_e32 v56, 24, v42
	v_and_b32_e32 v46, 0xf00, v48
	v_and_b32_e32 v47, 0xf000, v50
	v_sub_u32_e32 v42, v42, v55
	v_and_b32_e32 v41, 0xf00000, v41
	v_and_b32_e32 v40, 0xf0000, v40
	v_and_or_b32 v34, v34, 15, v45
	v_and_b32_e32 v48, 0xf0000, v52
	v_and_b32_e32 v49, 0xf00000, v54
	v_or3_b32 v35, v35, v40, v41
	v_lshlrev_b32_e32 v40, 20, v42
	v_bfe_i32 v42, v36, 0, 4
	v_or3_b32 v34, v34, v46, v47
	v_and_b32_e32 v37, 0xf000000, v56
	v_lshlrev_b32_e32 v41, 28, v36
	v_sub_u32_sdwa v36, v36, v42 dst_sel:BYTE_3 dst_unused:UNUSED_PAD src0_sel:DWORD src1_sel:DWORD
	v_or3_b32 v34, v34, v48, v49
	v_and_b32_e32 v40, 0xf000000, v40
	v_or3_b32 v214, v34, v37, v41
	v_and_b32_e32 v34, 0xf0000000, v36
	v_or3_b32 v215, v35, v40, v34
	v_mul_f32_e32 v34, v38, v148
	v_rndne_f32_e32 v34, v34
	v_cvt_i32_f32_e32 v56, v34
	v_mul_f32_e32 v34, v38, v149
	v_rndne_f32_e32 v34, v34
	v_cvt_i32_f32_e32 v34, v34
	v_mul_f32_e32 v37, v38, v146
	v_rndne_f32_e32 v37, v37
	v_cvt_i32_f32_e32 v37, v37
	v_bfe_i32 v35, v56, 0, 4
	v_bfe_i32 v36, v34, 0, 4
	v_sub_u32_e32 v35, v56, v35
	v_sub_u32_e32 v36, v34, v36
	v_lshlrev_b32_e32 v34, 4, v34
	v_lshrrev_b32_e32 v35, 4, v35
	v_and_b32_e32 v57, 0xf0, v34
	v_and_b32_e32 v34, 0xf0, v36
	v_and_or_b32 v74, v35, 15, v34
	v_bfe_i32 v34, v37, 0, 4
	v_sub_u32_e32 v75, v37, v34
	v_lshlrev_b32_e32 v34, 8, v37
	v_and_b32_e32 v76, 0xf00, v34
	v_mul_f32_e32 v34, v38, v147
	v_rndne_f32_e32 v34, v34
	v_cvt_i32_f32_e32 v77, v34
	v_readlane_b32 s11, v210, 16
	s_lshl_b32 s11, s11, 10
	s_add_u32 s48, s72, s11
	s_addc_u32 s49, s73, 0
	global_load_dwordx4 v[40:43], v219, s[48:49]
	v_readlane_b32 s37, v210, 17
	s_lshl_b32 s37, s37, 10
	s_add_u32 s50, s72, s37
	s_addc_u32 s51, s73, 0
	global_load_dwordx4 v[44:47], v219, s[50:51]
	v_readlane_b32 s11, v210, 18
	s_lshl_b32 s11, s11, 10
	s_add_u32 s48, s72, s11
	s_addc_u32 s49, s73, 0
	global_load_dwordx4 v[48:51], v219, s[48:49]
	v_readlane_b32 s37, v210, 19
	s_lshl_b32 s37, s37, 10
	s_add_u32 s50, s72, s37
	s_addc_u32 s51, s73, 0
	global_load_dwordx4 v[52:55], v219, s[50:51]
	v_readlane_b32 s11, v210, 20
	s_lshl_b32 s11, s11, 10
	s_add_u32 s48, s72, s11
	s_addc_u32 s49, s73, 0
	global_load_dwordx4 v[58:61], v219, s[48:49]
	v_readlane_b32 s37, v210, 21
	s_lshl_b32 s37, s37, 10
	s_add_u32 s50, s72, s37
	s_addc_u32 s51, s73, 0
	global_load_dwordx4 v[62:65], v219, s[50:51]
	v_readlane_b32 s11, v210, 22
	s_lshl_b32 s11, s11, 10
	s_add_u32 s48, s72, s11
	s_addc_u32 s49, s73, 0
	global_load_dwordx4 v[66:69], v219, s[48:49]
	v_readlane_b32 s37, v210, 23
	s_lshl_b32 s37, s37, 10
	s_add_u32 s50, s72, s37
	s_addc_u32 s51, s73, 0
	global_load_dwordx4 v[70:73], v219, s[50:51]
	v_bfe_i32 v35, v77, 0, 4
	v_sub_u32_e32 v35, v77, v35
	v_lshlrev_b32_e32 v34, 4, v75
	v_lshlrev_b32_e32 v35, 8, v35
	v_and_b32_e32 v34, 0xf00, v34
	v_mul_f32_e32 v37, v38, v144
	v_and_b32_e32 v35, 0xf000, v35
	v_rndne_f32_e32 v37, v37
	v_or3_b32 v34, v74, v34, v35
	v_mul_f32_e32 v74, v38, v145
	v_cvt_i32_f32_e32 v37, v37
	v_rndne_f32_e32 v74, v74
	v_cvt_i32_f32_e32 v74, v74
	v_lshlrev_b32_e32 v36, 12, v77
	v_mul_f32_e32 v77, v38, v140
	v_mul_f32_e32 v39, 0x42a00000, v38
	v_rndne_f32_e32 v77, v77
	v_mul_f32_e32 v38, v38, v141
	v_bfe_i32 v35, v37, 0, 4
	v_cvt_i32_f32_e32 v77, v77
	v_rndne_f32_e32 v38, v38
	v_sub_u32_e32 v35, v37, v35
	v_bfe_i32 v75, v74, 0, 4
	v_cvt_i32_f32_e32 v38, v38
	v_lshlrev_b32_e32 v35, 12, v35
	v_sub_u32_sdwa v75, v74, v75 dst_sel:WORD_1 dst_unused:UNUSED_PAD src0_sel:DWORD src1_sel:DWORD
	v_and_b32_e32 v36, 0xf000, v36
	v_lshlrev_b32_e32 v37, 16, v37
	v_and_b32_e32 v35, 0xf0000, v35
	v_lshlrev_b32_e32 v74, 20, v74
	v_and_b32_e32 v75, 0xf00000, v75
	v_and_or_b32 v56, v56, 15, v57
	v_and_b32_e32 v37, 0xf0000, v37
	v_and_b32_e32 v74, 0xf00000, v74
	v_or3_b32 v34, v34, v35, v75
	v_bfe_i32 v35, v77, 0, 4
	v_lshlrev_b32_e32 v75, 24, v77
	v_or3_b32 v36, v56, v76, v36
	v_sub_u32_e32 v35, v77, v35
	v_and_b32_e32 v75, 0xf000000, v75
	v_lshlrev_b32_e32 v77, 28, v38
	v_or3_b32 v36, v36, v37, v74
	v_or3_b32 v216, v36, v75, v77
	v_div_scale_f32 v36, s[0:1], v39, v39, 1.0
	v_rcp_f32_e32 v37, v36
	v_bfe_i32 v78, v38, 0, 4
	v_lshlrev_b32_e32 v35, 20, v35
	v_sub_u32_sdwa v38, v38, v78 dst_sel:BYTE_3 dst_unused:UNUSED_PAD src0_sel:DWORD src1_sel:DWORD
	v_and_b32_e32 v35, 0xf000000, v35
	v_and_b32_e32 v38, 0xf0000000, v38
	v_or3_b32 v217, v34, v35, v38
	v_fma_f32 v34, -v36, v37, 1.0
	v_fmac_f32_e32 v37, v34, v37
	v_div_scale_f32 v34, vcc, 1.0, v39, 1.0
	v_mul_f32_e32 v35, v34, v37
	v_fma_f32 v38, -v36, v35, v34
	v_fmac_f32_e32 v35, v38, v37
	v_fma_f32 v34, -v36, v35, v34
	v_div_fmas_f32 v34, v34, v37, v35
	v_div_fixup_f32 v218, v34, v39, 1.0
	v_mov_b32_e32 v240, 0
	v_mov_b32_e32 v241, 0
	v_mov_b32_e32 v242, 0
	v_mov_b32_e32 v243, 0
	v_mov_b32_e32 v244, 0
	v_mov_b32_e32 v245, 0
	v_mov_b32_e32 v246, 0
	v_mov_b32_e32 v247, 0
	v_mov_b32_e32 v248, 0
	v_mov_b32_e32 v249, 0
	v_mov_b32_e32 v124, 0
	v_mov_b32_e32 v125, 0
	s_mov_b32 s8, 0
	.p2align	6

; template <class Epi, class Sched, bool ALIGN_EPI = false, bool SP2 = false>
; __device__ __forceinline__ void gemm_phase(PG8_LAS unsigned char* lds, const Gemm g, const Sched& S, const Epi& E) {
;     ...
;         const bool has_next = S.next(ui + 1, nxt);
;         const char* nA = has_next ? (const char*)g.A + (size_t)nxt.pm * tstep : cA; const char* nB = has_next ? (const char*)g.Bt + (size_t)nxt.pn * tstep : cB;
;         for (int t = 0; t < nt; t += 2) {
;             const bool last = (t == nt - 2);
;             const char* a1 = cA + (size_t)(t + 1) * kstep;
;             const char* a2 = last ? nA : cA + (size_t)(t + 2) * kstep; const char* b2 = last ? nB : cB + (size_t)(t + 2) * kstep;
;     ...
;         for (int a = 0; a < 2; ++a)
; #pragma unroll
;             for (int b = 0; b < 2; ++b)
; #pragma unroll
;                 for (int m = 0; m < 4; ++m)
; #pragma unroll
;                     for (int n = 0; n < 2; ++n) acc[a][b][m][n] = (f32x4){0.f, 0.f, 0.f, 0.f};
;         cur = nxt; cA = nA; cB = nB; ++ui;
.LBB0_447:
	s_ashr_i32 s37, s36, 31
	s_lshl_b64 s[38:39], s[36:37], 19
	v_readlane_b32 s42, v250, 27
	v_readlane_b32 s43, v250, 28
	s_add_u32 s38, s42, s38
	s_addc_u32 s39, s43, s39
	s_and_b64 s[42:43], s[40:41], exec
	s_cselect_b32 s1, s39, s47
	s_cselect_b32 s37, s38, s46
	s_ashr_i32 s11, s10, 31
	s_lshl_b64 s[42:43], s[10:11], 19
	v_readlane_b32 s52, v250, 21
	v_readlane_b32 s53, v250, 22
	s_add_u32 s42, s52, s42
	s_addc_u32 s43, s53, s43
	s_and_b64 s[52:53], s[40:41], exec
	s_cselect_b32 s11, s43, s49
	s_cselect_b32 s66, s42, s48
	s_add_u32 s46, s46, 0x40080
	s_addc_u32 s47, s47, 0
	s_add_u32 s67, s48, 0x100
	v_mov_b32_e32 v2, 0
	s_addc_u32 s68, s49, 0
	s_mov_b32 s69, -2
	v_mov_b32_e32 v3, v2
	v_mov_b32_e32 v4, v2
	v_mov_b32_e32 v5, v2
	v_mov_b32_e32 v6, v2
	v_mov_b32_e32 v7, v2
	v_mov_b32_e32 v8, v2
	v_mov_b32_e32 v9, v2
	v_mov_b32_e32 v18, v2
	v_mov_b32_e32 v19, v2
	v_mov_b32_e32 v20, v2
	v_mov_b32_e32 v21, v2
	v_mov_b32_e32 v22, v2
	v_mov_b32_e32 v23, v2
	v_mov_b32_e32 v24, v2
	v_mov_b32_e32 v25, v2
	v_mov_b32_e32 v34, v2
	v_mov_b32_e32 v35, v2
	v_mov_b32_e32 v36, v2
	v_mov_b32_e32 v37, v2
	v_mov_b32_e32 v38, v2
	v_mov_b32_e32 v39, v2
	v_mov_b32_e32 v40, v2
	v_mov_b32_e32 v41, v2
	v_mov_b32_e32 v50, v2
	v_mov_b32_e32 v51, v2
	v_mov_b32_e32 v52, v2
	v_mov_b32_e32 v53, v2
	v_mov_b32_e32 v54, v2
	v_mov_b32_e32 v55, v2
	v_mov_b32_e32 v56, v2
	v_mov_b32_e32 v57, v2
	v_mov_b32_e32 v10, v2
	v_mov_b32_e32 v11, v2
	v_mov_b32_e32 v12, v2
	v_mov_b32_e32 v13, v2
	v_mov_b32_e32 v14, v2
	v_mov_b32_e32 v15, v2
	v_mov_b32_e32 v16, v2
	v_mov_b32_e32 v17, v2
	v_mov_b32_e32 v26, v2
	v_mov_b32_e32 v27, v2
	v_mov_b32_e32 v28, v2
	v_mov_b32_e32 v29, v2
	v_mov_b32_e32 v30, v2
	v_mov_b32_e32 v31, v2
	v_mov_b32_e32 v32, v2
	v_mov_b32_e32 v33, v2
	v_mov_b32_e32 v42, v2
	v_mov_b32_e32 v43, v2
	v_mov_b32_e32 v44, v2
	v_mov_b32_e32 v45, v2
	v_mov_b32_e32 v46, v2
	v_mov_b32_e32 v47, v2
	v_mov_b32_e32 v48, v2
	v_mov_b32_e32 v49, v2
	v_mov_b32_e32 v58, v2
	v_mov_b32_e32 v59, v2
	v_mov_b32_e32 v60, v2
	v_mov_b32_e32 v61, v2
	v_mov_b32_e32 v62, v2
	v_mov_b32_e32 v63, v2
	v_mov_b32_e32 v64, v2
	v_mov_b32_e32 v65, v2
	v_mov_b32_e32 v66, v2
	v_mov_b32_e32 v67, v2
	v_mov_b32_e32 v68, v2
	v_mov_b32_e32 v69, v2
	v_mov_b32_e32 v70, v2
	v_mov_b32_e32 v71, v2
	v_mov_b32_e32 v72, v2
	v_mov_b32_e32 v73, v2
	v_mov_b32_e32 v78, v2
	v_mov_b32_e32 v79, v2
	v_mov_b32_e32 v80, v2
	v_mov_b32_e32 v81, v2
	v_mov_b32_e32 v86, v2
	v_mov_b32_e32 v87, v2
	v_mov_b32_e32 v88, v2
	v_mov_b32_e32 v89, v2
	v_mov_b32_e32 v94, v2
	v_mov_b32_e32 v95, v2
	v_mov_b32_e32 v96, v2
	v_mov_b32_e32 v97, v2
	v_mov_b32_e32 v102, v2
	v_mov_b32_e32 v103, v2
	v_mov_b32_e32 v104, v2
	v_mov_b32_e32 v105, v2
	v_mov_b32_e32 v110, v2
	v_mov_b32_e32 v111, v2
	v_mov_b32_e32 v112, v2
	v_mov_b32_e32 v113, v2
	v_mov_b32_e32 v118, v2
	v_mov_b32_e32 v119, v2
	v_mov_b32_e32 v120, v2
	v_mov_b32_e32 v121, v2
	v_mov_b32_e32 v74, v2
	v_mov_b32_e32 v75, v2
	v_mov_b32_e32 v76, v2
	v_mov_b32_e32 v77, v2
	v_mov_b32_e32 v82, v2
	v_mov_b32_e32 v83, v2
	v_mov_b32_e32 v84, v2
	v_mov_b32_e32 v85, v2
	v_mov_b32_e32 v90, v2
	v_mov_b32_e32 v91, v2
	v_mov_b32_e32 v92, v2
	v_mov_b32_e32 v93, v2
	v_mov_b32_e32 v98, v2
	v_mov_b32_e32 v99, v2
	v_mov_b32_e32 v100, v2
	v_mov_b32_e32 v101, v2
	v_mov_b32_e32 v106, v2
	v_mov_b32_e32 v107, v2
	v_mov_b32_e32 v108, v2
	v_mov_b32_e32 v109, v2
	v_mov_b32_e32 v114, v2
	v_mov_b32_e32 v115, v2
	v_mov_b32_e32 v116, v2
	v_mov_b32_e32 v117, v2
	v_mov_b32_e32 v122, v2
	v_mov_b32_e32 v123, v2
	v_mov_b32_e32 v124, v2
	v_mov_b32_e32 v125, v2
	v_mov_b32_e32 v126, v2
	v_mov_b32_e32 v127, v2
	v_mov_b32_e32 v128, v2
	v_mov_b32_e32 v129, v2
	.p2align	6
